# NA loop per-tile LDS-DMA address arithmetic scalarised on top of v36 (two per-unit lane-offset sets + saddr loads); paired check because quick timings drift
# speedup vs baseline: 1.0009x; 1.0009x over previous
.LBB0_541:
	s_or_b64 exec, exec, s[0:1]
	s_waitcnt lgkmcnt(0)
	s_and_b32 s5, s13, 15
	s_lshl_b32 s4, s5, 2
	s_min_u32 s6, s4, 57
	s_lshr_b32 s1, s13, 7
	s_add_i32 s0, s4, -4
	s_add_i32 s6, s6, 7
	s_cmp_eq_u32 s5, 0
	s_cselect_b32 s36, 0, s0
	s_cselect_b32 s0, 8, s6
	s_sub_i32 s0, s0, s36
	s_add_i32 s6, s0, 1
	s_and_b32 s37, s6, -2
	s_lshl_b32 s6, s1, 12
	s_addk_i32 s6, 0x2000
	s_lshl_b32 s5, s5, 8
	s_or_b32 s8, s6, s5
	s_lshl_b32 s5, s36, 6
	s_add_i32 s5, s5, s6
	s_mul_hi_u32 s6, s5, 0x8200
	s_mul_i32 s5, s5, 0x8200
	s_add_u32 s5, s39, s5
	v_readlane_b32 s7, v254, 24
	s_addc_u32 s6, s7, s6
	s_add_u32 s20, s5, 0x4000
	s_addc_u32 s21, s6, 0
	s_lshl_b32 s33, s12, 7
	s_add_u32 s22, s5, 0x4800
	s_addc_u32 s23, s6, 0
	s_lshl_b32 s1, s1, 20
	v_readlane_b32 s5, v254, 56
	s_or_b32 s1, s1, s5
	s_add_u32 s24, s17, s1
	s_addc_u32 s25, s18, 0
	s_add_u32 s34, s19, s1
	v_readlane_b32 s1, v254, 51
	s_addc_u32 s35, s1, 0
	s_mul_i32 s5, s8, 0x8200
	s_mul_hi_u32 s1, s8, 0x8200
	s_add_u32 s5, s39, s5
	s_addc_u32 s6, s7, s1
	s_lshl_b32 s1, s12, 8
	s_add_u32 s5, s5, s1
	s_addc_u32 s7, s6, 0
	v_mov_b32_e32 v136, v0
	s_barrier
	v_writelane_b32 v254, s8, 60
	s_add_u32 s6, s5, 0x3800
	s_addc_u32 s7, s7, 0
	v_readfirstlane_b32 s8, v136
	s_ashr_i32 s5, s8, 6
	v_and_b32_e32 v171, 31, v136
	s_lshl_b32 s14, s5, 5
	v_bfe_u32 v170, v136, 5, 1
	v_or_b32_e32 v2, s14, v171
	v_mov_b64_e32 v[4:5], s[6:7]
	v_mad_i64_i32 v[4:5], s[6:7], v2, s16, v[4:5]
	v_lshlrev_b32_e32 v2, 4, v170
	v_lshl_add_u64 v[4:5], v[4:5], 0, v[2:3]
	global_load_dwordx4 v[52:55], v[4:5], off offset:224
	global_load_dwordx4 v[56:59], v[4:5], off offset:192
	global_load_dwordx4 v[60:63], v[4:5], off offset:160
	global_load_dwordx4 v[64:67], v[4:5], off offset:128
	global_load_dwordx4 v[108:111], v[4:5], off offset:96
	global_load_dwordx4 v[112:115], v[4:5], off offset:64
	global_load_dwordx4 v[116:119], v[4:5], off offset:32
	global_load_dwordx4 v[120:123], v[4:5], off
	v_and_b32_e32 v137, 32, v136
	global_load_dwordx4 v[48:51], v137, s[44:45]
	global_load_dwordx4 v[44:47], v137, s[44:45] offset:16
	global_load_dwordx4 v[40:43], v137, s[44:45] offset:64
	global_load_dwordx4 v[36:39], v137, s[44:45] offset:80
	global_load_dwordx4 v[32:35], v137, s[44:45] offset:128
	global_load_dwordx4 v[28:31], v137, s[44:45] offset:144
	global_load_dwordx4 v[24:27], v137, s[44:45] offset:192
	global_load_dwordx4 v[20:23], v137, s[44:45] offset:208
	global_load_dwordx4 v[16:19], v137, s[44:45] offset:256
	global_load_dwordx4 v[12:15], v137, s[44:45] offset:272
	global_load_dwordx4 v[8:11], v137, s[44:45] offset:320
	global_load_dwordx4 v[4:7], v137, s[44:45] offset:336
	s_and_b32 s6, s8, 0x3fffffc0
	s_lshl_b32 s6, s6, 2
	s_add_i32 s6, s6, 0
	s_add_i32 s15, s6, 0x14000
	s_lshl_b32 s5, s5, 10
	s_cmp_gt_i32 s0, 0
	s_cselect_b64 s[6:7], -1, 0
	s_sub_i32 s38, 0, s37
	s_and_b64 s[8:9], s[6:7], exec
	s_movk_i32 s8, 0x4100
	s_cselect_b32 s9, s20, s24
	s_cselect_b32 s0, 0, s38
	s_cselect_b32 s10, s8, 0x400
	s_cselect_b32 s8, s21, s25
	s_add_u32 s9, s9, s1
	v_ashrrev_i32_e32 v173, 4, v136
	s_addc_u32 s8, s8, 0
	s_and_b64 s[6:7], s[6:7], exec
	s_cselect_b32 s7, s22, s34
	s_cselect_b32 s6, s23, s35
	s_add_u32 s11, s7, s1
	s_mul_hi_u32 s1, s0, s10
	s_mul_i32 s0, s0, s10
	s_addc_u32 s12, s6, 0
	s_lshl_b64 s[0:1], s[0:1], 7
	s_add_u32 s6, s9, s0
	s_addc_u32 s7, s8, s1
	s_add_u32 s0, s11, s0
	s_addc_u32 s1, s12, s1
	s_add_i32 s39, s5, 0
	s_add_i32 m0, s39, 0x8000
	v_mov_b32_e32 v151, v3
	v_and_b32_e32 v172, 63, v136
	v_cmp_gt_u32_e64 s[12:13], 32, v172
	v_lshl_add_u32 v177, v171, 2, s15
	s_waitcnt vmcnt(19)
	v_lshlrev_b32_e32 v74, 16, v52
	v_and_b32_e32 v75, 0xffff0000, v52
	v_lshlrev_b32_e32 v70, 16, v53
	v_and_b32_e32 v71, 0xffff0000, v53
	s_waitcnt vmcnt(15)
	v_lshlrev_b32_e32 v100, 16, v111
	v_and_b32_e32 v101, 0xffff0000, v111
	s_waitcnt vmcnt(13)
	v_lshlrev_b32_e32 v128, 16, v117
	v_and_b32_e32 v129, 0xffff0000, v117
	v_lshlrev_b32_e32 v132, 16, v116
	v_and_b32_e32 v133, 0xffff0000, v116
	s_waitcnt vmcnt(12)
	v_lshlrev_b32_e32 v116, 16, v123
	v_and_b32_e32 v117, 0xffff0000, v123
	v_and_b32_e32 v123, 0xffff0000, v120
	v_lshlrev_b32_e32 v134, 16, v122
	v_and_b32_e32 v135, 0xffff0000, v122
	v_lshlrev_b32_e32 v122, 16, v120
	v_mul_f32_e32 v52, v123, v123
	v_lshlrev_b32_e32 v104, 16, v110
	v_and_b32_e32 v105, 0xffff0000, v110
	v_lshlrev_b32_e32 v110, 16, v115
	v_and_b32_e32 v111, 0xffff0000, v115
	v_lshlrev_b32_e32 v124, 16, v113
	v_and_b32_e32 v125, 0xffff0000, v113
	v_lshlrev_b32_e32 v126, 16, v114
	v_and_b32_e32 v127, 0xffff0000, v114
	v_lshlrev_b32_e32 v114, 16, v112
	v_and_b32_e32 v115, 0xffff0000, v112
	v_lshlrev_b32_e32 v112, 16, v119
	v_and_b32_e32 v113, 0xffff0000, v119
	v_lshlrev_b32_e32 v130, 16, v118
	v_and_b32_e32 v131, 0xffff0000, v118
	v_lshlrev_b32_e32 v118, 16, v121
	v_and_b32_e32 v119, 0xffff0000, v121
	v_pk_fma_f32 v[52:53], v[122:123], v[122:123], v[52:53] op_sel_hi:[1,1,0]
	v_lshlrev_b32_e32 v72, 16, v54
	v_and_b32_e32 v73, 0xffff0000, v54
	v_pk_fma_f32 v[52:53], v[118:119], v[118:119], v[52:53]
	v_mul_f32_e32 v54, v119, v119
	v_pk_add_f32 v[52:53], v[54:55], v[52:53] op_sel_hi:[0,1]
	v_pk_fma_f32 v[52:53], v[134:135], v[134:135], v[52:53]
	v_mul_f32_e32 v54, v135, v135
	v_pk_add_f32 v[52:53], v[54:55], v[52:53] op_sel_hi:[0,1]
	v_pk_fma_f32 v[52:53], v[116:117], v[116:117], v[52:53]
	v_mul_f32_e32 v54, v117, v117
	v_pk_add_f32 v[52:53], v[54:55], v[52:53] op_sel_hi:[0,1]
	v_pk_fma_f32 v[52:53], v[132:133], v[132:133], v[52:53]
	v_mul_f32_e32 v54, v133, v133
	v_pk_add_f32 v[52:53], v[54:55], v[52:53] op_sel_hi:[0,1]
	v_pk_fma_f32 v[52:53], v[128:129], v[128:129], v[52:53]
	v_mul_f32_e32 v54, v129, v129
	v_pk_add_f32 v[52:53], v[54:55], v[52:53] op_sel_hi:[0,1]
	v_pk_fma_f32 v[52:53], v[130:131], v[130:131], v[52:53]
	v_mul_f32_e32 v54, v131, v131
	v_pk_add_f32 v[52:53], v[54:55], v[52:53] op_sel_hi:[0,1]
	v_pk_fma_f32 v[52:53], v[112:113], v[112:113], v[52:53]
	v_mul_f32_e32 v54, v113, v113
	v_pk_add_f32 v[52:53], v[54:55], v[52:53] op_sel_hi:[0,1]
	v_pk_fma_f32 v[52:53], v[114:115], v[114:115], v[52:53]
	v_mul_f32_e32 v54, v115, v115
	v_pk_add_f32 v[52:53], v[54:55], v[52:53] op_sel_hi:[0,1]
	v_pk_fma_f32 v[52:53], v[124:125], v[124:125], v[52:53]
	v_mul_f32_e32 v54, v125, v125
	v_pk_add_f32 v[52:53], v[54:55], v[52:53] op_sel_hi:[0,1]
	v_pk_fma_f32 v[52:53], v[126:127], v[126:127], v[52:53]
	v_mul_f32_e32 v54, v127, v127
	v_pk_add_f32 v[52:53], v[54:55], v[52:53] op_sel_hi:[0,1]
	v_pk_fma_f32 v[52:53], v[110:111], v[110:111], v[52:53]
	v_mul_f32_e32 v54, v111, v111
	v_lshlrev_b32_e32 v106, 16, v108
	v_and_b32_e32 v107, 0xffff0000, v108
	v_pk_add_f32 v[52:53], v[54:55], v[52:53] op_sel_hi:[0,1]
	v_pk_fma_f32 v[52:53], v[106:107], v[106:107], v[52:53]
	v_mul_f32_e32 v54, v107, v107
	v_lshlrev_b32_e32 v102, 16, v109
	v_and_b32_e32 v103, 0xffff0000, v109
	v_pk_add_f32 v[52:53], v[54:55], v[52:53] op_sel_hi:[0,1]
	v_pk_fma_f32 v[52:53], v[102:103], v[102:103], v[52:53]
	v_mul_f32_e32 v54, v103, v103
	v_pk_add_f32 v[52:53], v[54:55], v[52:53] op_sel_hi:[0,1]
	v_pk_fma_f32 v[52:53], v[104:105], v[104:105], v[52:53]
	v_mul_f32_e32 v54, v105, v105
	v_pk_add_f32 v[52:53], v[54:55], v[52:53] op_sel_hi:[0,1]
	v_pk_fma_f32 v[52:53], v[100:101], v[100:101], v[52:53]
	v_mul_f32_e32 v54, v101, v101
	v_lshlrev_b32_e32 v98, 16, v64
	v_and_b32_e32 v99, 0xffff0000, v64
	v_pk_add_f32 v[52:53], v[54:55], v[52:53] op_sel_hi:[0,1]
	v_pk_fma_f32 v[52:53], v[98:99], v[98:99], v[52:53]
	v_mul_f32_e32 v54, v99, v99
	v_lshlrev_b32_e32 v94, 16, v65
	v_and_b32_e32 v95, 0xffff0000, v65
	v_pk_add_f32 v[52:53], v[54:55], v[52:53] op_sel_hi:[0,1]
	v_pk_fma_f32 v[52:53], v[94:95], v[94:95], v[52:53]
	v_mul_f32_e32 v54, v95, v95
	v_lshlrev_b32_e32 v96, 16, v66
	v_and_b32_e32 v97, 0xffff0000, v66
	v_pk_add_f32 v[52:53], v[54:55], v[52:53] op_sel_hi:[0,1]
	v_pk_fma_f32 v[52:53], v[96:97], v[96:97], v[52:53]
	v_mul_f32_e32 v54, v97, v97
	v_lshlrev_b32_e32 v92, 16, v67
	v_and_b32_e32 v93, 0xffff0000, v67
	v_pk_add_f32 v[52:53], v[54:55], v[52:53] op_sel_hi:[0,1]
	v_pk_fma_f32 v[52:53], v[92:93], v[92:93], v[52:53]
	v_mul_f32_e32 v54, v93, v93
	v_lshlrev_b32_e32 v90, 16, v60
	v_and_b32_e32 v91, 0xffff0000, v60
	v_pk_add_f32 v[52:53], v[54:55], v[52:53] op_sel_hi:[0,1]
	v_pk_fma_f32 v[52:53], v[90:91], v[90:91], v[52:53]
	v_mul_f32_e32 v54, v91, v91
	v_lshlrev_b32_e32 v86, 16, v61
	v_and_b32_e32 v87, 0xffff0000, v61
	v_pk_add_f32 v[52:53], v[54:55], v[52:53] op_sel_hi:[0,1]
	v_pk_fma_f32 v[52:53], v[86:87], v[86:87], v[52:53]
	v_mul_f32_e32 v54, v87, v87
	v_lshlrev_b32_e32 v88, 16, v62
	v_and_b32_e32 v89, 0xffff0000, v62
	v_pk_add_f32 v[52:53], v[54:55], v[52:53] op_sel_hi:[0,1]
	v_pk_fma_f32 v[52:53], v[88:89], v[88:89], v[52:53]
	v_mul_f32_e32 v54, v89, v89
	v_lshlrev_b32_e32 v84, 16, v63
	v_and_b32_e32 v85, 0xffff0000, v63
	v_pk_add_f32 v[52:53], v[54:55], v[52:53] op_sel_hi:[0,1]
	v_pk_fma_f32 v[52:53], v[84:85], v[84:85], v[52:53]
	v_mul_f32_e32 v54, v85, v85
	v_lshlrev_b32_e32 v82, 16, v56
	v_and_b32_e32 v83, 0xffff0000, v56
	v_pk_add_f32 v[52:53], v[54:55], v[52:53] op_sel_hi:[0,1]
	v_pk_fma_f32 v[52:53], v[82:83], v[82:83], v[52:53]
	v_mul_f32_e32 v54, v83, v83
	v_lshlrev_b32_e32 v78, 16, v57
	v_and_b32_e32 v79, 0xffff0000, v57
	v_pk_add_f32 v[52:53], v[54:55], v[52:53] op_sel_hi:[0,1]
	v_pk_fma_f32 v[52:53], v[78:79], v[78:79], v[52:53]
	v_mul_f32_e32 v54, v79, v79
	v_lshlrev_b32_e32 v80, 16, v58
	v_and_b32_e32 v81, 0xffff0000, v58
	v_pk_add_f32 v[52:53], v[54:55], v[52:53] op_sel_hi:[0,1]
	v_pk_fma_f32 v[52:53], v[80:81], v[80:81], v[52:53]
	v_mul_f32_e32 v54, v81, v81
	v_lshlrev_b32_e32 v76, 16, v59
	v_and_b32_e32 v77, 0xffff0000, v59
	v_pk_add_f32 v[52:53], v[54:55], v[52:53] op_sel_hi:[0,1]
	v_pk_fma_f32 v[52:53], v[76:77], v[76:77], v[52:53]
	v_mul_f32_e32 v54, v77, v77
	v_pk_add_f32 v[52:53], v[54:55], v[52:53] op_sel_hi:[0,1]
	v_pk_fma_f32 v[52:53], v[74:75], v[74:75], v[52:53]
	v_mul_f32_e32 v54, v75, v75
	v_pk_add_f32 v[52:53], v[54:55], v[52:53] op_sel_hi:[0,1]
	v_pk_fma_f32 v[52:53], v[70:71], v[70:71], v[52:53]
	v_mul_f32_e32 v54, v71, v71
	v_pk_add_f32 v[52:53], v[54:55], v[52:53] op_sel_hi:[0,1]
	v_pk_fma_f32 v[52:53], v[72:73], v[72:73], v[52:53]
	v_mul_f32_e32 v54, v73, v73
	v_lshlrev_b32_e32 v68, 16, v55
	v_and_b32_e32 v69, 0xffff0000, v55
	v_pk_add_f32 v[52:53], v[54:55], v[52:53] op_sel_hi:[0,1]
	v_pk_fma_f32 v[52:53], v[68:69], v[68:69], v[52:53]
	v_mul_f32_e32 v54, v69, v69
	v_pk_add_f32 v[52:53], v[54:55], v[52:53] op_sel_hi:[0,1]
	v_mov_b32_e32 v53, v52
	s_nop 1
	v_permlane32_swap_b32_e32 v52, v53
	v_add_f32_e32 v52, v52, v53
	v_fmamk_f32 v52, v52, 0x3c000000, v198
	v_mul_f32_e32 v53, 0x4b800000, v52
	v_cmp_gt_f32_e32 vcc, s46, v52
	s_nop 1
	v_cndmask_b32_e32 v52, v52, v53, vcc
	v_rsq_f32_e32 v108, v52
	global_load_dwordx4 v[64:67], v137, s[44:45] offset:384
	global_load_dwordx4 v[60:63], v137, s[44:45] offset:400
	global_load_dwordx4 v[56:59], v137, s[44:45] offset:448
	global_load_dwordx4 v[52:55], v137, s[44:45] offset:464
	v_mul_f32_e32 v109, 0x45800000, v108
	v_cndmask_b32_e32 v108, v108, v109, vcc
	v_pk_mul_f32 v[120:121], v[108:109], v[122:123] op_sel_hi:[0,1]
	s_waitcnt vmcnt(15)
	v_pk_mul_f32 v[48:49], v[48:49], v[120:121]
	v_pk_mul_f32 v[120:121], v[108:109], v[134:135] op_sel_hi:[0,1]
	s_waitcnt vmcnt(14)
	v_pk_mul_f32 v[44:45], v[44:45], v[120:121]
	v_pk_mul_f32 v[118:119], v[108:109], v[118:119] op_sel_hi:[0,1]
	v_pk_mul_f32 v[50:51], v[50:51], v[118:119]
	v_cvt_pk_bf16_f32 v118, v44, v45
	v_pk_mul_f32 v[44:45], v[108:109], v[132:133] op_sel_hi:[0,1]
	s_waitcnt vmcnt(13)
	v_pk_mul_f32 v[40:41], v[40:41], v[44:45]
	v_pk_mul_f32 v[44:45], v[108:109], v[130:131] op_sel_hi:[0,1]
	s_waitcnt vmcnt(12)
	v_pk_mul_f32 v[36:37], v[36:37], v[44:45]
	v_pk_mul_f32 v[44:45], v[108:109], v[128:129] op_sel_hi:[0,1]
	v_cvt_pk_bf16_f32 v122, v36, v37
	v_pk_mul_f32 v[36:37], v[108:109], v[114:115] op_sel_hi:[0,1]
	s_waitcnt vmcnt(11)
	v_pk_mul_f32 v[32:33], v[32:33], v[36:37]
	v_pk_mul_f32 v[36:37], v[108:109], v[126:127] op_sel_hi:[0,1]
	v_pk_mul_f32 v[42:43], v[42:43], v[44:45]
	v_pk_mul_f32 v[44:45], v[108:109], v[112:113] op_sel_hi:[0,1]
	s_waitcnt vmcnt(10)
	v_pk_mul_f32 v[36:37], v[28:29], v[36:37]
	v_pk_mul_f32 v[28:29], v[108:109], v[124:125] op_sel_hi:[0,1]
	v_pk_mul_f32 v[38:39], v[38:39], v[44:45]
	v_pk_mul_f32 v[34:35], v[34:35], v[28:29]
	v_pk_mul_f32 v[28:29], v[108:109], v[110:111] op_sel_hi:[0,1]
	v_cvt_pk_bf16_f32 v123, v38, v39
	v_pk_mul_f32 v[30:31], v[30:31], v[28:29]
	v_bfe_u32 v28, v136, 2, 2
	v_lshrrev_b32_e32 v38, 1, v136
	v_cvt_pk_bf16_f32 v120, v40, v41
	v_and_or_b32 v38, v38, 8, v28
	v_and_b32_e32 v28, 0x60, v136
	v_lshlrev_b32_e32 v39, 3, v136
	v_lshrrev_b32_e32 v40, 1, v173
	v_cvt_pk_bf16_f32 v121, v42, v43
	v_and_or_b32 v42, v39, 24, v28
	v_and_b32_e32 v39, -16, v173
	v_and_b32_e32 v40, 4, v40
	v_or3_b32 v174, v40, v39, v38
	v_add_u32_e32 v39, 0x200, v136
	v_ashrrev_i32_e32 v175, 4, v39
	v_lshrrev_b32_e32 v40, 1, v175
	v_and_b32_e32 v29, 15, v136
	v_and_b32_e32 v39, -16, v175
	v_and_b32_e32 v40, 4, v40
	v_bitop3_b32 v28, v173, v29, 7 bitop3:0x6c
	v_or3_b32 v176, v40, v39, v38
	v_mul_hi_i32_i24_sdwa v39, s10, sext(v173) dst_sel:DWORD dst_unused:UNUSED_PAD src0_sel:DWORD src1_sel:WORD_0
	v_mul_i32_i24_sdwa v38, s10, sext(v173) dst_sel:DWORD dst_unused:UNUSED_PAD src0_sel:DWORD src1_sel:WORD_0
	v_lshl_add_u64 v[38:39], v[38:39], 1, s[6:7]
	v_lshlrev_b32_e32 v40, 4, v28
	v_mov_b32_e32 v41, v3
	v_lshl_add_u64 v[38:39], v[38:39], 0, v[40:41]
	global_load_lds_dwordx4 v[38:39], off
	v_mad_i64_i32 v[38:39], s[8:9], s10, v174, 0
	v_lshl_add_u64 v[38:39], v[38:39], 1, s[0:1]
	v_lshlrev_b32_e32 v150, 1, v42
	v_lshl_add_u64 v[38:39], v[38:39], 0, v[150:151]
	s_mov_b32 m0, s39
	v_bitop3_b32 v29, v175, v29, 7 bitop3:0x6c
	global_load_lds_dwordx4 v[38:39], off
	v_mul_hi_i32_i24_sdwa v39, s10, sext(v175) dst_sel:DWORD dst_unused:UNUSED_PAD src0_sel:DWORD src1_sel:WORD_0
	v_mul_i32_i24_sdwa v38, s10, sext(v175) dst_sel:DWORD dst_unused:UNUSED_PAD src0_sel:DWORD src1_sel:WORD_0
	v_lshl_add_u64 v[38:39], v[38:39], 1, s[6:7]
	v_lshlrev_b32_e32 v40, 4, v29
	v_lshl_add_u64 v[38:39], v[38:39], 0, v[40:41]
	s_add_i32 m0, s39, 0xa000
	v_cvt_pk_bf16_f32 v127, v30, v31
	global_load_lds_dwordx4 v[38:39], off
	v_mad_i64_i32 v[38:39], s[6:7], s10, v176, 0
	v_lshl_add_u64 v[38:39], v[38:39], 1, s[0:1]
	v_lshl_add_u64 v[38:39], v[38:39], 0, v[150:151]
	s_add_i32 m0, s39, 0x2000
	v_pk_mul_f32 v[30:31], v[108:109], v[106:107] op_sel_hi:[0,1]
	global_load_lds_dwordx4 v[38:39], off
	s_waitcnt vmcnt(0)
	v_pk_mul_f32 v[24:25], v[24:25], v[30:31]
	v_pk_mul_f32 v[30:31], v[108:109], v[104:105] op_sel_hi:[0,1]
	v_pk_mul_f32 v[20:21], v[20:21], v[30:31]
	v_pk_mul_f32 v[30:31], v[108:109], v[102:103] op_sel_hi:[0,1]
	v_cvt_pk_bf16_f32 v130, v20, v21
	v_pk_mul_f32 v[20:21], v[108:109], v[98:99] op_sel_hi:[0,1]
	v_pk_mul_f32 v[16:17], v[16:17], v[20:21]
	v_pk_mul_f32 v[20:21], v[108:109], v[96:97] op_sel_hi:[0,1]
	v_pk_mul_f32 v[12:13], v[12:13], v[20:21]
	v_pk_mul_f32 v[20:21], v[108:109], v[94:95] op_sel_hi:[0,1]
	v_cvt_pk_bf16_f32 v134, v12, v13
	v_pk_mul_f32 v[12:13], v[108:109], v[90:91] op_sel_hi:[0,1]
	v_pk_mul_f32 v[8:9], v[12:13], v[8:9]
	v_pk_mul_f32 v[12:13], v[108:109], v[88:89] op_sel_hi:[0,1]
	v_pk_mul_f32 v[4:5], v[12:13], v[4:5]
	v_pk_mul_f32 v[12:13], v[108:109], v[86:87] op_sel_hi:[0,1]
	v_pk_mul_f32 v[10:11], v[12:13], v[10:11]
	v_pk_mul_f32 v[12:13], v[108:109], v[84:85] op_sel_hi:[0,1]
	v_pk_mul_f32 v[6:7], v[12:13], v[6:7]
	v_cvt_pk_bf16_f32 v136, v8, v9
	v_cvt_pk_bf16_f32 v137, v10, v11
	v_cvt_pk_bf16_f32 v138, v4, v5
	v_cvt_pk_bf16_f32 v139, v6, v7
	v_pk_mul_f32 v[4:5], v[108:109], v[82:83] op_sel_hi:[0,1]
	v_pk_mul_f32 v[6:7], v[108:109], v[80:81] op_sel_hi:[0,1]
	v_pk_mul_f32 v[8:9], v[108:109], v[78:79] op_sel_hi:[0,1]
	v_pk_mul_f32 v[10:11], v[108:109], v[76:77] op_sel_hi:[0,1]
	v_pk_mul_f32 v[4:5], v[4:5], v[64:65]
	v_pk_mul_f32 v[6:7], v[6:7], v[60:61]
	v_pk_mul_f32 v[8:9], v[8:9], v[66:67]
	v_pk_mul_f32 v[10:11], v[10:11], v[62:63]
	v_pk_mul_f32 v[116:117], v[108:109], v[116:117] op_sel_hi:[0,1]
	v_pk_mul_f32 v[26:27], v[26:27], v[30:31]
	v_pk_mul_f32 v[30:31], v[108:109], v[100:101] op_sel_hi:[0,1]
	v_pk_mul_f32 v[18:19], v[18:19], v[20:21]
	v_pk_mul_f32 v[20:21], v[108:109], v[92:93] op_sel_hi:[0,1]
	v_cvt_pk_bf16_f32 v140, v4, v5
	v_cvt_pk_bf16_f32 v141, v8, v9
	v_cvt_pk_bf16_f32 v142, v6, v7
	v_cvt_pk_bf16_f32 v143, v10, v11
	v_pk_mul_f32 v[4:5], v[108:109], v[74:75] op_sel_hi:[0,1]
	v_pk_mul_f32 v[6:7], v[108:109], v[72:73] op_sel_hi:[0,1]
	v_pk_mul_f32 v[8:9], v[108:109], v[70:71] op_sel_hi:[0,1]
	v_pk_mul_f32 v[10:11], v[108:109], v[68:69] op_sel_hi:[0,1]
	s_waitcnt vmcnt(0)
	v_pk_mul_f32 v[46:47], v[46:47], v[116:117]
	v_pk_mul_f32 v[22:23], v[22:23], v[30:31]
	v_pk_mul_f32 v[14:15], v[14:15], v[20:21]
	v_pk_mul_f32 v[4:5], v[4:5], v[56:57]
	v_pk_mul_f32 v[6:7], v[6:7], v[52:53]
	v_pk_mul_f32 v[8:9], v[8:9], v[58:59]
	v_pk_mul_f32 v[10:11], v[10:11], v[54:55]
	v_cvt_pk_bf16_f32 v116, v48, v49
	v_cvt_pk_bf16_f32 v117, v50, v51
	v_cvt_pk_bf16_f32 v119, v46, v47
	v_cvt_pk_bf16_f32 v124, v32, v33
	v_cvt_pk_bf16_f32 v125, v34, v35
	v_cvt_pk_bf16_f32 v126, v36, v37
	v_cvt_pk_bf16_f32 v128, v24, v25
	v_cvt_pk_bf16_f32 v129, v26, v27
	v_cvt_pk_bf16_f32 v131, v22, v23
	v_cvt_pk_bf16_f32 v132, v16, v17
	v_cvt_pk_bf16_f32 v133, v18, v19
	v_cvt_pk_bf16_f32 v135, v14, v15
	v_cvt_pk_bf16_f32 v144, v4, v5
	v_cvt_pk_bf16_f32 v145, v8, v9
	v_cvt_pk_bf16_f32 v146, v6, v7
	v_cvt_pk_bf16_f32 v147, v10, v11
	s_cmp_lt_i32 s37, -7
	s_waitcnt lgkmcnt(0)
	s_barrier
	s_cbranch_scc1 .LBB0_626
	s_sub_i32 s0, 63, s36
	v_writelane_b32 v254, s0, 61
	v_readlane_b32 s0, v253, 51
	s_add_i32 s0, s4, s0
	v_and_or_b32 v7, s14, 32, v171
	v_lshlrev_b32_e32 v8, 4, v171
	s_min_i32 s1, s0, 60
	v_and_b32_e32 v9, 0x70, v8
	v_bitop3_b32 v179, v2, v8, s89 bitop3:0x78
	v_min_u32_e32 v8, 56, v7
	s_add_i32 s40, s37, 8
	s_add_i32 s1, s1, -4
	v_add_u32_e32 v8, -8, v8
	v_cmp_lt_u32_e32 vcc, 7, v7
	s_cmp_gt_u32 s0, 3
	v_writelane_b32 v254, s14, 62
	v_cndmask_b32_e32 v68, 0, v8, vcc
	v_lshlrev_b32_e32 v8, 2, v170
	s_cselect_b32 s16, s1, 0
	v_cmp_ge_i32_e64 s[0:1], v8, v68
	v_or_b32_e32 v10, 32, v8
	v_add_u32_e32 v70, -16, v68
	v_writelane_b32 v254, s0, 63
	v_add_u32_e32 v69, 16, v68
	v_lshlrev_b32_e32 v4, 1, v172
	v_writelane_b32 v255, s1, 0
	v_cmp_ge_i32_e64 s[0:1], v10, v68
	v_sub_u32_e32 v10, v10, v7
	v_med3_i32 v188, v10, -15, 15
	v_writelane_b32 v255, s0, 1
	v_or_b32_e32 v10, 1, v8
	v_sub_u32_e32 v11, v10, v7
	v_writelane_b32 v255, s1, 2
	v_cmp_lt_i32_e64 s[0:1], v8, v70
	v_max_i32_e32 v189, -15, v11
	v_or_b32_e32 v11, 33, v8
	v_writelane_b32 v255, s0, 3
	v_bitop3_b32 v182, v2, v9, s83 bitop3:0x36
	v_or_b32_e32 v71, 25, v8
	v_writelane_b32 v255, s1, 4
	v_cmp_ge_i32_e64 s[0:1], v10, v68
	v_and_b32_e32 v4, 32, v4
	v_lshlrev_b32_e32 v5, 4, v172
	v_writelane_b32 v255, s0, 5
	v_lshlrev_b32_e32 v6, 3, v172
	v_bitop3_b32 v183, v2, v9, s86 bitop3:0x36
	v_writelane_b32 v255, s1, 6
	v_cmp_ge_i32_e64 s[0:1], v11, v68
	v_bitop3_b32 v184, v2, v9, s88 bitop3:0x36
	v_bitop3_b32 v185, v2, v9, s87 bitop3:0x36
	v_writelane_b32 v255, s0, 7
	v_or_b32_e32 v72, 26, v8
	v_or_b32_e32 v73, 27, v8
	v_writelane_b32 v255, s1, 8
	v_cmp_lt_i32_e64 s[0:1], v10, v70
	v_sub_u32_e32 v10, v11, v7
	v_med3_i32 v190, v10, -15, 15
	v_writelane_b32 v255, s0, 9
	v_or_b32_e32 v10, 2, v8
	v_sub_u32_e32 v11, v10, v7
	v_writelane_b32 v255, s1, 10
	v_cmp_ge_i32_e64 s[0:1], v10, v68
	v_max_i32_e32 v191, -15, v11
	v_or_b32_e32 v11, 34, v8
	v_writelane_b32 v255, s0, 11
	v_lshlrev_b32_e32 v20, 3, v28
	v_lshlrev_b32_e32 v21, 3, v29
	v_writelane_b32 v255, s1, 12
	v_cmp_ge_i32_e64 s[0:1], v11, v68
	v_and_b32_e32 v5, 0xc0, v5
	v_bitop3_b32 v180, v2, v9, 32 bitop3:0x36
	v_writelane_b32 v255, s0, 13
	v_bitop3_b32 v181, v2, v9, 64 bitop3:0x36
	v_bitop3_b32 v186, v2, v9, s90 bitop3:0x36
	v_writelane_b32 v255, s1, 14
	v_cmp_lt_i32_e64 s[0:1], v10, v70
	v_sub_u32_e32 v10, v11, v7
	v_med3_i32 v192, v10, -15, 15
	v_writelane_b32 v255, s0, 15
	v_or_b32_e32 v10, 3, v8
	v_sub_u32_e32 v11, v10, v7
	v_writelane_b32 v255, s1, 16
	v_cmp_ge_i32_e64 s[0:1], v10, v68
	v_max_i32_e32 v193, -15, v11
	v_or_b32_e32 v11, 35, v8
	v_writelane_b32 v255, s0, 17
	v_sub_u32_e32 v9, v8, v7
	v_add_u32_e32 v221, s15, v2
	v_writelane_b32 v255, s1, 18
	v_cmp_ge_i32_e64 s[0:1], v11, v68
	v_and_or_b32 v2, v6, s91, v4
	v_mov_b32_e32 v18, v3
	v_writelane_b32 v255, s0, 19
	v_mov_b32_e32 v19, v3
	v_max_i32_e32 v187, -15, v9
	v_writelane_b32 v255, s1, 20
	v_cmp_lt_i32_e64 s[0:1], v10, v70
	v_sub_u32_e32 v10, v11, v7
	v_med3_i32 v194, v10, -15, 15
	v_writelane_b32 v255, s0, 21
	v_or_b32_e32 v10, 8, v8
	v_sub_u32_e32 v11, v10, v7
	v_writelane_b32 v255, s1, 22
	v_cmp_ge_i32_e64 s[0:1], v10, v68
	v_max_i32_e32 v195, -15, v11
	v_or_b32_e32 v11, 40, v8
	v_writelane_b32 v255, s0, 23
	v_min_i32_e32 v206, 0xffffffdf, v9
	v_min_i32_e32 v208, 0xffffffde, v9
	v_writelane_b32 v255, s1, 24
	v_cmp_ge_i32_e64 s[0:1], v11, v68
	v_min_i32_e32 v210, 0xffffffdd, v9
	v_min_i32_e32 v212, 0xffffffdc, v9
	v_writelane_b32 v255, s0, 25
	v_min_i32_e32 v214, 0xffffffd7, v9
	v_min_i32_e32 v216, 0xffffffd6, v9
	v_writelane_b32 v255, s1, 26
	v_cmp_lt_i32_e64 s[0:1], v10, v70
	v_sub_u32_e32 v10, v11, v7
	v_med3_i32 v196, v10, -15, 15
	v_or_b32_e32 v10, 9, v8
	v_sub_u32_e32 v11, v10, v7
	v_writelane_b32 v255, s0, 27
	v_max_i32_e32 v197, -15, v11
	v_or_b32_e32 v11, 41, v8
	v_writelane_b32 v255, s1, 28
	v_cmp_ge_i32_e64 s[0:1], v10, v68
	v_cmp_lt_i32_e64 s[50:51], v10, v70
	v_sub_u32_e32 v10, v11, v7
	v_med3_i32 v200, v10, -15, 15
	v_or_b32_e32 v10, 10, v8
	v_cmp_ge_i32_e64 s[48:49], v11, v68
	v_sub_u32_e32 v11, v10, v7
	v_max_i32_e32 v201, -15, v11
	v_or_b32_e32 v11, 42, v8
	v_cmp_ge_i32_e64 s[52:53], v10, v68
	v_cmp_lt_i32_e64 s[56:57], v10, v70
	v_sub_u32_e32 v10, v11, v7
	v_med3_i32 v202, v10, -15, 15
	v_or_b32_e32 v10, 11, v8
	v_cmp_ge_i32_e64 s[54:55], v11, v68
	v_sub_u32_e32 v11, v10, v7
	v_max_i32_e32 v203, -15, v11
	v_or_b32_e32 v11, 43, v8
	v_cmp_ge_i32_e64 s[58:59], v10, v68
	v_cmp_lt_i32_e64 s[62:63], v10, v70
	v_sub_u32_e32 v10, v11, v7
	v_med3_i32 v204, v10, -15, 15
	v_or_b32_e32 v10, 16, v8
	v_cmp_ge_i32_e64 s[60:61], v11, v68
	v_cmp_ge_i32_e32 vcc, v10, v68
	v_sub_u32_e32 v11, v10, v7
	v_cmp_lt_i32_e64 s[64:65], v10, v70
	v_or_b32_e32 v10, 17, v8
	v_writelane_b32 v255, s0, 29
	v_med3_i32 v205, v11, -15, 15
	v_cmp_ge_i32_e64 s[66:67], v10, v68
	v_cmp_lt_u32_e64 s[68:69], v10, v69
	v_sub_u32_e32 v11, v10, v7
	v_cmp_lt_i32_e64 s[70:71], v10, v70
	v_or_b32_e32 v10, 18, v8
	v_writelane_b32 v255, s1, 30
	v_cmp_lt_i32_e64 s[0:1], v8, v68
	v_med3_i32 v207, v11, -15, 15
	v_cmp_ge_i32_e64 s[72:73], v10, v68
	v_cmp_lt_u32_e64 s[74:75], v10, v69
	v_sub_u32_e32 v11, v10, v7
	v_cmp_lt_i32_e64 s[76:77], v10, v70
	v_or_b32_e32 v10, 19, v8
	s_and_b64 s[28:29], vcc, s[0:1]
	v_med3_i32 v209, v11, -15, 15
	v_cmp_ge_i32_e64 s[78:79], v10, v68
	v_cmp_lt_u32_e64 s[80:81], v10, v69
	v_sub_u32_e32 v11, v10, v7
	v_cmp_lt_i32_e64 s[82:83], v10, v70
	v_or_b32_e32 v10, 24, v8
	v_readlane_b32 s0, v253, 52
	v_med3_i32 v211, v11, -15, 15
	v_cmp_ge_i32_e64 s[84:85], v10, v68
	v_cmp_lt_u32_e64 s[86:87], v10, v69
	v_sub_u32_e32 v11, v10, v7
	s_add_i32 s0, s0, s36
	v_cmp_lt_i32_e64 s[88:89], v10, v70
	v_sub_u32_e32 v10, v71, v7
	s_sub_i32 s0, s0, s4
	v_med3_i32 v215, v10, -15, 15
	v_sub_u32_e32 v10, v72, v7
	v_sub_u32_e32 v7, v73, v7
	v_med3_i32 v213, v11, -15, 15
	v_med3_i32 v217, v10, -15, 15
	v_min_i32_e32 v218, 0xffffffd5, v9
	v_med3_i32 v219, v7, -15, 15
	v_min_i32_e32 v220, 0xffffffd4, v9
	v_add3_u32 v222, v5, 0, v2
	s_mul_i32 s0, s0, 31
	v_mov_b32_e32 v4, v3
	v_mov_b32_e32 v5, v3
	v_mov_b32_e32 v6, v3
	v_mov_b32_e32 v7, v3
	v_mov_b32_e32 v8, v3
	v_mov_b32_e32 v9, v3
	v_mov_b32_e32 v10, v3
	v_mov_b32_e32 v11, v3
	v_mov_b32_e32 v12, v3
	v_mov_b32_e32 v13, v3
	v_mov_b32_e32 v14, v3
	v_mov_b32_e32 v15, v3
	v_mov_b32_e32 v16, v3
	v_mov_b32_e32 v17, v3
	v_lshlrev_b32_e32 v2, 1, v20
	v_lshlrev_b32_e32 v152, 1, v21
	v_mov_b64_e32 v[66:67], v[18:19]
	v_mov_b64_e32 v[50:51], v[18:19]
	v_mov_b64_e32 v[34:35], v[18:19]
	s_mov_b32 s41, 1
	s_add_i32 s17, s16, 8
	v_lshlrev_b32_e32 v178, 8, v171
	v_writelane_b32 v255, s15, 31
	s_add_i32 s18, s0, 0xd9
	v_mov_b32_e32 v224, 0
	v_mov_b32_e32 v223, 0xf149f2ca
	v_mov_b64_e32 v[64:65], v[16:17]
	v_mov_b64_e32 v[62:63], v[14:15]
	v_mov_b64_e32 v[60:61], v[12:13]
	v_mov_b64_e32 v[58:59], v[10:11]
	v_mov_b64_e32 v[56:57], v[8:9]
	v_mov_b64_e32 v[54:55], v[6:7]
	v_mov_b64_e32 v[52:53], v[4:5]
	v_mov_b64_e32 v[48:49], v[16:17]
	v_mov_b64_e32 v[46:47], v[14:15]
	v_mov_b64_e32 v[44:45], v[12:13]
	v_mov_b64_e32 v[42:43], v[10:11]
	v_mov_b64_e32 v[40:41], v[8:9]
	v_mov_b64_e32 v[38:39], v[6:7]
	v_mov_b64_e32 v[36:37], v[4:5]
	v_mov_b64_e32 v[32:33], v[16:17]
	v_mov_b64_e32 v[30:31], v[14:15]
	v_mov_b64_e32 v[28:29], v[12:13]
	v_mov_b64_e32 v[26:27], v[10:11]
	v_mov_b64_e32 v[24:25], v[8:9]
	v_mov_b64_e32 v[22:23], v[6:7]
	v_mov_b64_e32 v[20:21], v[4:5]
	v_cmp_ge_i32_e64 s[90:91], v71, v68
	v_cmp_lt_u32_e64 s[92:93], v71, v69
	v_cmp_lt_i32_e64 s[94:95], v71, v70
	v_cmp_ge_i32_e64 s[96:97], v72, v68
	v_cmp_lt_u32_e64 s[14:15], v72, v69
	v_cmp_lt_i32_e64 s[10:11], v72, v70
	v_cmp_ge_i32_e64 s[0:1], v73, v68
	v_cmp_lt_u32_e64 s[8:9], v73, v69
	v_cmp_lt_i32_e64 s[6:7], v73, v70
	v_bfe_i32 v235, v173, 0, 16
	v_bfe_i32 v240, v175, 0, 16
	v_mov_b32_e32 v234, 0x8200
	v_mad_u32_u24 v226, v235, v234, v2
	v_mad_u32_u24 v227, v174, v234, v150
	v_mad_u32_u24 v228, v240, v234, v152
	v_mad_u32_u24 v229, v176, v234, v150
	v_lshl_add_u32 v230, v235, 11, v2
	v_lshl_add_u32 v231, v174, 11, v150
	v_lshl_add_u32 v232, v240, 11, v152
	v_lshl_add_u32 v233, v176, 11, v150
	s_branch .LBB0_546

.LBB0_551:
	s_lshl_b32 s5, s33, 1
	s_add_u32 vcc_lo, s26, s5
	s_addc_u32 vcc_hi, s27, 0
	s_add_u32 s5, s30, s5
	s_mul_hi_u32 s27, s47, s4
	s_mul_i32 s26, s47, s4
	s_addc_u32 s31, s31, 0
	s_lshl_b64 s[26:27], s[26:27], 7
	s_add_u32 s30, s5, s26
	s_addc_u32 s31, s31, s27
	s_add_u32 s26, vcc_lo, s26
	s_addc_u32 s27, vcc_hi, s27
	s_lshl_b32 s5, s19, 14
	s_xor_b32 s5, s5, 0x4000
	s_add_i32 s47, s39, s5
	s_add_i32 m0, s47, 0x8000
	s_cmp_eq_u32 s4, 0x400
	s_cbranch_scc1 .Lna_dma_b
	global_load_lds_dwordx4 v226, s[30:31]
	s_mov_b32 m0, s47
	s_nop 0
	global_load_lds_dwordx4 v227, s[26:27]
	s_add_i32 m0, s47, 0xa000
	s_nop 0
	global_load_lds_dwordx4 v228, s[30:31]
	s_add_i32 m0, s47, 0x2000
	s_nop 0
	global_load_lds_dwordx4 v229, s[26:27]
	s_branch .LBB0_552
.Lna_dma_b:
	global_load_lds_dwordx4 v230, s[30:31]
	s_mov_b32 m0, s47
	s_nop 0
	global_load_lds_dwordx4 v231, s[26:27]
	s_add_i32 m0, s47, 0xa000
	s_nop 0
	global_load_lds_dwordx4 v232, s[30:31]
	s_add_i32 m0, s47, 0x2000
	s_nop 0
	global_load_lds_dwordx4 v233, s[26:27]
